# 20 sample-attention units on the 4 GEMM CUs that have no 6th unit (blockIdx 220..223), on top of late W_in panels + 72 units deferred to P3
# speedup vs baseline: 1.0094x; 1.0045x over previous
; __global__ void __launch_bounds__(NTHR, 2) hybrid_fwd(Args args) {
;     ...
;       pg8::gemm_phase<Epi1, Sched1, true, true>(F.lds, DM, DM, S, E); }
;     if ((int)blockIdx.x >= NAS_FREE_FROM && (int)gridDim.x == 256) {
;         Frame F = make_frame(lds);
;         if (F.tid < 64) { unsigned* fl = (unsigned*)(F.ws + WS_CTL) + CW_QREADY; unsigned sp = 0;
;             while (__hip_atomic_load(fl, __ATOMIC_RELAXED, __HIP_MEMORY_SCOPE_AGENT) < (unsigned)G1_SPECIAL) { __builtin_amdgcn_s_sleep(4); if (++sp > (1u << 22)) break; }
;             __builtin_amdgcn_fence(__ATOMIC_ACQUIRE, "agent"); }
;         asm volatile("s_waitcnt vmcnt(0)" ::: "memory"); __syncthreads();
;         for (int u = (int)blockIdx.x - NAS_FREE_FROM; u < NAS_UNITS; u += 256 - NAS_FREE_FROM) attn_sample_head_unit(F, u);
;     }
.LBB0_271:
	s_mov_b32 s98, 1
	s_sub_i32 s99, s2, 0xdc
	s_cmp_lt_u32 s99, 4
	s_cbranch_scc0 .Lnot_idle
	s_mov_b32 s98, 0x81
	s_branch .Lside_attn
.Lnot_idle:
	s_cmp_gt_i32 s2, 0xdf
	s_cselect_b64 s[4:5], -1, 0
	s_and_b64 s[6:7], s[4:5], s[38:39]
	v_cndmask_b32_e64 v1, 0, 1, s[6:7]
	v_cmp_ne_u32_e64 s[4:5], 1, v1
	s_andn2_b64 vcc, exec, s[6:7]
	s_cbranch_vccnz .LBB0_311
	s_mov_b32 s98, 0
	s_branch .LBB0_311

; __global__ void __launch_bounds__(NTHR, 2) hybrid_fwd(Args args) {
;     ...
;     if ((int)blockIdx.x >= NAS_FREE_FROM && (int)gridDim.x == 256) {
;         Frame F = make_frame(lds);
;         if (F.tid < 64) { unsigned* fl = (unsigned*)(F.ws + WS_CTL) + CW_QREADY; unsigned sp = 0;
;             while (__hip_atomic_load(fl, __ATOMIC_RELAXED, __HIP_MEMORY_SCOPE_AGENT) < (unsigned)G1_SPECIAL) { __builtin_amdgcn_s_sleep(4); if (++sp > (1u << 22)) break; }
;             __builtin_amdgcn_fence(__ATOMIC_ACQUIRE, "agent"); }
;         asm volatile("s_waitcnt vmcnt(0)" ::: "memory"); __syncthreads();
;         for (int u = (int)blockIdx.x - NAS_FREE_FROM; u < NAS_UNITS; u += 256 - NAS_FREE_FROM) attn_sample_head_unit(F, u);
.LBB0_282:
	s_or_b64 exec, exec, s[6:7]
	s_waitcnt vmcnt(0)
	s_cmpk_gt_i32 s2, 0x2df
	s_waitcnt vmcnt(0) lgkmcnt(0)
	s_barrier
	s_cbranch_scc1 .LBB0_311
	s_ashr_i32 s20, s12, 6
	s_lshl_b32 s6, s20, 2
	s_add_i32 s12, s6, 0
	s_sub_i32 s29, s2, 0xe0
	s_movk_i32 s100, 0x20
	s_movk_i32 s101, 0x184
	s_bitcmp1_b32 s98, 6
	s_cbranch_scc0 .Lattn_p1
	s_add_i32 s29, s2, 0xdc
	s_movk_i32 s100, 36
	s_movk_i32 s101, 0x1dc
.Lattn_p1:
	s_bitcmp1_b32 s98, 7
	s_cbranch_scc0 .Lattn_p1b
	s_add_i32 s29, s2, 0xc8
	s_movk_i32 s100, 4
	s_movk_i32 s101, 0x1b4

; __global__ void __launch_bounds__(NTHR, 2) hybrid_fwd(Args args) {
;     ...
;     if ((int)blockIdx.x >= NAS_FREE_FROM && (int)gridDim.x == 256) {
;         Frame F = make_frame(lds);
;         if (F.tid < 64) { unsigned* fl = (unsigned*)(F.ws + WS_CTL) + CW_QREADY; unsigned sp = 0;
;             while (__hip_atomic_load(fl, __ATOMIC_RELAXED, __HIP_MEMORY_SCOPE_AGENT) < (unsigned)G1_SPECIAL) { __builtin_amdgcn_s_sleep(4); if (++sp > (1u << 22)) break; }
;             __builtin_amdgcn_fence(__ATOMIC_ACQUIRE, "agent"); }
;         asm volatile("s_waitcnt vmcnt(0)" ::: "memory"); __syncthreads();
;         for (int u = (int)blockIdx.x - NAS_FREE_FROM; u < NAS_UNITS; u += 256 - NAS_FREE_FROM) attn_sample_head_unit(F, u);
;     }
;     {
;         constexpr int NFREE = 256 - NAS_FREE_FROM, N3 = NAS_UNITS - 2 * NFREE, NLATE = NFREE - N3;
;         const int idx = (int)blockIdx.x - NAS_FREE_FROM - N3;
;         if (idx >= 0 && (int)gridDim.x == 256) { Frame F = make_frame(lds);
;             p0_items(F, NITEMS_EARLY, NITEMS, idx * NWAVES + F.wave, NLATE * NWAVES);
;             p0_pool_pad(F, idx * NTHR + F.tid, NLATE * NTHR); p0_pool_frag(F, idx * NTHR + F.tid, NLATE * NTHR); }
;     }
;     if ((int)blockIdx.x >= NAS_FREE_FROM && (int)gridDim.x == 256) {
;         Frame F = make_frame(lds); states_copy_rows(F, ((int)blockIdx.x - NAS_FREE_FROM) * NWAVES + F.wave, (256 - NAS_FREE_FROM) * NWAVES); }
.LBB0_311:
	s_bitcmp1_b32 s98, 7
	s_cbranch_scc0 .Lnot_idle2
	s_mov_b32 s98, 1
	s_branch .Lnot_idle
